# prologue: layer-0 weight transposes redistributed so workgroups that run two modulation GEMV items get fewer transpose items (2 vs ~3.9 per wave)
# speedup vs baseline: 1.0138x; 1.0138x over previous
.LBB0_88:
	s_load_dwordx2 s[8:9], s[80:81], 0x90
	s_load_dwordx2 s[10:11], s[80:81], 0xa0
	v_mov_b32_e32 v4, v228
	s_lshl_b32 s78, s2, 3
	s_waitcnt lgkmcnt(0)
	s_barrier
	s_movk_i32 s4, 0x1780
	v_ashrrev_i32_e32 v3, 6, v4
	s_cmpk_lt_i32 s2, 0x80
	s_cselect_b32 s28, 0, 0x400
	s_add_i32 s28, s78, s28
	v_add_u32_e32 v2, s28, v3
	s_lshl_b32 s76, s42, 3
	v_cmp_gt_i32_e32 vcc, s4, v2
	s_and_saveexec_b64 s[12:13], vcc
	s_cbranch_execz .LBB0_119
	v_lshl_add_u32 v8, v3, 14, 0
	v_bfe_u32 v3, v4, 5, 1
	v_and_b32_e32 v17, 31, v4
	v_bfe_u32 v33, v4, 3, 3
	v_lshlrev_b32_e32 v4, 3, v4
	v_lshlrev_b32_e32 v14, 2, v17
	v_mul_u32_u24_e32 v5, 0x84, v3
	v_and_b32_e32 v4, 56, v4
	v_add3_u32 v32, v8, v14, v5
	v_mul_u32_u24_e32 v9, 0x84, v4
	v_lshlrev_b32_e32 v4, 1, v4
	v_mov_b32_e32 v5, 0
	v_lshl_add_u64 v[12:13], s[40:41], 0, v[4:5]
	s_mov_b64 s[4:5], 0x4600000
	v_lshl_add_u64 v[6:7], v[12:13], 0, s[4:5]
	v_lshlrev_b32_e32 v4, 2, v33
	s_mov_b64 s[4:5], 0x2600000
	v_add3_u32 v34, v8, v9, v4
	v_lshl_add_u64 v[8:9], v[12:13], 0, s[4:5]
	s_mov_b64 s[4:5], 0x1e00000
	v_lshl_add_u64 v[10:11], v[12:13], 0, s[4:5]
	s_mov_b64 s[4:5], 0x800000
	v_lshl_add_u64 v[12:13], v[12:13], 0, s[4:5]
	s_load_dwordx2 s[4:5], s[80:81], 0x68
	v_or_b32_e32 v36, 16, v33
	v_or_b32_e32 v37, 24, v33
	v_not_b32_e32 v4, 30
	v_lshl_add_u32 v40, v36, 1, v4
	v_lshl_add_u32 v41, v37, 1, v4
	v_mov_b32_e32 v4, 0xfffffa00
	v_or_b32_e32 v35, 8, v33
	v_mov_b32_e32 v15, v5
	v_lshl_add_u32 v16, v2, 5, v4
	v_mov_b32_e32 v4, 0x1e100
	v_lshlrev_b32_e32 v38, 1, v33
	v_lshlrev_b32_e32 v39, 1, v35
	s_waitcnt lgkmcnt(0)
	v_lshl_add_u64 v[14:15], s[4:5], 0, v[14:15]
	s_mov_b32 s28, 0x8000
	v_lshl_add_u32 v42, v2, 1, v4
	s_movk_i32 s29, 0x800
	s_mov_b64 s[20:21], 0
	s_movk_i32 s30, 0x57f
	s_movk_i32 s31, 0x77f
	s_movk_i32 s34, 0xf7f
	s_mov_b32 s35, 0x2e8ba2e9
	s_movk_i32 s45, 0xffa8
	s_movk_i32 s46, 0xf500
	s_movk_i32 s47, 0x2c00
	s_movk_i32 s48, 0x17f
	s_movk_i32 s49, 0x177f
	s_cmpk_lt_i32 s2, 0x80
	s_cselect_b32 s49, 0x7ff, s49
	v_add_u32_e32 v43, 0x400, v32
	v_add_u32_e32 v44, 0x800, v32
	v_add_u32_e32 v46, 0xc00, v32
	v_add_u32_e32 v47, 0x1000, v32
	v_add_u32_e32 v48, 0x1400, v32
	v_add_u32_e32 v49, 0x1800, v32
	v_add_u32_e32 v50, 0x1c00, v32
	s_branch .LBB0_92

.LBB0_91:
	s_or_b64 exec, exec, s[22:23]
	v_add_u32_e32 v2, 0x400, v2
	v_cmp_lt_i32_e32 vcc, s49, v2
	v_add_u32_e32 v16, s28, v16
	s_or_b64 s[20:21], vcc, s[20:21]
	v_add_u32_e32 v42, s29, v42
	s_andn2_b64 exec, exec, s[20:21]
	s_cbranch_execz .LBB0_119
